# attention loops: first-iteration entry blocks moved out of line so the per-step X path falls through without a taken branch
# speedup vs baseline: 1.0009x; 1.0009x over previous
.LBB0_623:
	s_add_i32 s57, s9, 0
	s_add_i32 s4, s57, s94
	v_add_u32_e32 v80, s4, v162
	v_add_u32_e32 v84, v80, v146
	ds_read_b128 v[80:83], v84
	ds_read_b128 v[220:223], v84 offset:32
	ds_read_b128 v[136:139], v84 offset:4608
	ds_read_b128 v[224:227], v84 offset:4640
	ds_read_b128 v[166:169], v84 offset:64
	ds_read_b128 v[170:173], v84 offset:96
	ds_read_b128 v[178:181], v84 offset:4672
	ds_read_b128 v[182:185], v84 offset:4704
	s_branch .Lv1p_body
.LBB0_622:
	v_add3_u32 v165, s57, v143, v163
	ds_read_b128 v[190:193], v165 offset:18432
	ds_read_b128 v[194:197], v165 offset:18448
	ds_read_b128 v[128:131], v165 offset:23040
	ds_read_b128 v[132:135], v165 offset:23056
	ds_read_b128 v[136:139], v165 offset:27648
	ds_read_b128 v[166:169], v165 offset:27664
	ds_read_b128 v[170:173], v165 offset:32256
	ds_read_b128 v[178:181], v165 offset:32272
	v_exp_f32_e32 v96, v96
	v_exp_f32_e32 v97, v97
	v_exp_f32_e32 v98, v98
	v_exp_f32_e32 v99, v99
	v_exp_f32_e32 v100, v100
	v_add_f32_e32 v198, v97, v96
	v_exp_f32_e32 v101, v101
	v_add_f32_e32 v198, v98, v198
	v_exp_f32_e32 v102, v102
	v_add_f32_e32 v198, v99, v198
	v_exp_f32_e32 v103, v103
	v_add_f32_e32 v198, v100, v198
	v_exp_f32_e32 v104, v104
	v_add_f32_e32 v198, v101, v198
	v_exp_f32_e32 v105, v105
	v_add_f32_e32 v198, v102, v198
	v_exp_f32_e32 v106, v106
	v_add_f32_e32 v198, v103, v198
	v_exp_f32_e32 v107, v107
	v_add_f32_e32 v198, v104, v198
	v_exp_f32_e32 v108, v108
	v_add_f32_e32 v198, v105, v198
	v_exp_f32_e32 v109, v109
	v_add_f32_e32 v198, v106, v198
	v_exp_f32_e32 v110, v110
	v_add_f32_e32 v198, v107, v198
	v_exp_f32_e32 v111, v111
	v_add_f32_e32 v198, v108, v198
	v_add_f32_e32 v198, v109, v198
	v_add_f32_e32 v198, v110, v198
	v_add_f32_e32 v198, v111, v198
	v_add_f32_e32 v157, v157, v198
	v_cvt_pk_bf16_f32 v96, v96, v97
	v_cvt_pk_bf16_f32 v97, v98, v99
	v_cvt_pk_bf16_f32 v98, v100, v101
	v_cvt_pk_bf16_f32 v99, v102, v103
	v_cvt_pk_bf16_f32 v100, v104, v105
	v_cvt_pk_bf16_f32 v101, v106, v107
	v_cvt_pk_bf16_f32 v102, v108, v109
	v_cvt_pk_bf16_f32 v103, v110, v111
	s_waitcnt lgkmcnt(7)
	v_mfma_f32_32x32x16_bf16 v[48:63], v[190:193], v[96:99], v[48:63]
	v_exp_f32_e32 v174, v80
	v_exp_f32_e32 v175, v81
	v_exp_f32_e32 v182, v82
	v_exp_f32_e32 v183, v83
	v_add_f32_e32 v80, v175, v174
	v_add_f32_e32 v80, v182, v80
	s_waitcnt lgkmcnt(5)
	v_mfma_f32_32x32x16_bf16 v[0:15], v[128:131], v[96:99], v[0:15]
	v_add_f32_e32 v80, v183, v80
	v_mfma_f32_32x32x16_bf16 v[48:63], v[194:197], v[100:103], v[48:63]
	v_exp_f32_e32 v128, v84
	v_exp_f32_e32 v129, v85
	v_exp_f32_e32 v130, v86
	v_exp_f32_e32 v131, v87
	v_add_f32_e32 v80, v128, v80
	v_add_f32_e32 v80, v129, v80
	v_add_f32_e32 v80, v130, v80
	s_waitcnt lgkmcnt(4)
	v_mfma_f32_32x32x16_bf16 v[0:15], v[132:135], v[100:103], v[0:15]
	v_add_f32_e32 v184, v131, v80
	ds_read_b128 v[80:83], v165 offset:18496
	ds_read_b128 v[84:87], v165 offset:18512
	ds_read_b128 v[104:107], v165 offset:23104
	ds_read_b128 v[108:111], v165 offset:23120
	s_waitcnt lgkmcnt(7)
	v_mfma_f32_32x32x16_bf16 v[32:47], v[136:139], v[96:99], v[32:47]
	v_exp_f32_e32 v132, v88
	v_exp_f32_e32 v133, v89
	v_exp_f32_e32 v134, v90
	v_exp_f32_e32 v135, v91
	v_add_f32_e32 v88, v132, v184
	v_add_f32_e32 v88, v133, v88
	v_add_f32_e32 v88, v134, v88
	s_waitcnt lgkmcnt(5)
	v_mfma_f32_32x32x16_bf16 v[16:31], v[170:173], v[96:99], v[16:31]
	v_add_f32_e32 v88, v135, v88
	v_exp_f32_e32 v96, v92
	v_mfma_f32_32x32x16_bf16 v[32:47], v[166:169], v[100:103], v[32:47]
	v_exp_f32_e32 v97, v93
	v_exp_f32_e32 v98, v94
	v_exp_f32_e32 v95, v95
	v_add_f32_e32 v88, v96, v88
	v_add_f32_e32 v88, v97, v88
	v_add_f32_e32 v88, v98, v88
	v_add_f32_e32 v88, v95, v88
	s_waitcnt lgkmcnt(4)
	v_mfma_f32_32x32x16_bf16 v[16:31], v[178:181], v[100:103], v[16:31]
	v_add_f32_e32 v157, v157, v88
	v_cvt_pk_bf16_f32 v88, v174, v175
	v_cvt_pk_bf16_f32 v89, v182, v183
	v_cvt_pk_bf16_f32 v90, v128, v129
	v_cvt_pk_bf16_f32 v91, v130, v131
	v_cvt_pk_bf16_f32 v92, v132, v133
	v_cvt_pk_bf16_f32 v93, v134, v135
	v_cvt_pk_bf16_f32 v94, v96, v97
	v_cvt_pk_bf16_f32 v95, v98, v95
	ds_read_b128 v[96:99], v165 offset:27712
	ds_read_b128 v[100:103], v165 offset:27728
	ds_read_b128 v[128:131], v165 offset:32320
	ds_read_b128 v[132:135], v165 offset:32336
	s_waitcnt lgkmcnt(7)
	v_mfma_f32_32x32x16_bf16 v[48:63], v[80:83], v[88:91], v[48:63]
	s_waitcnt lgkmcnt(5)
	v_mfma_f32_32x32x16_bf16 v[0:15], v[104:107], v[88:91], v[0:15]
	s_add_i32 s4, s9, 0x9000
	s_cmp_lg_u32 s9, 0x12000
	s_cselect_b32 s9, s4, 0
	v_mfma_f32_32x32x16_bf16 v[48:63], v[84:87], v[92:95], v[48:63]
	s_waitcnt lgkmcnt(4)
	v_mfma_f32_32x32x16_bf16 v[0:15], v[108:111], v[92:95], v[0:15]
	s_add_i32 s4, s56, 1
	s_cmp_lg_u32 s56, 2
	s_cselect_b32 s56, s4, 0
	s_add_i32 s8, s8, 1
	s_add_i32 s87, s87, 64
	s_cmpk_lg_i32 s87, 0xfc0
	s_waitcnt lgkmcnt(0)
	s_barrier
	s_cbranch_scc0 .Lv1p_flush
	s_add_i32 s57, s9, 0
	s_add_i32 s4, s57, s94
	v_add_u32_e32 v80, s4, v162
	v_add_u32_e32 v84, v80, v146
	ds_read_b128 v[80:83], v84
	ds_read_b128 v[220:223], v84 offset:32
	ds_read_b128 v[136:139], v84 offset:4608
	ds_read_b128 v[224:227], v84 offset:4640
	ds_read_b128 v[166:169], v84 offset:64
	ds_read_b128 v[170:173], v84 offset:96
	ds_read_b128 v[178:181], v84 offset:4672
	ds_read_b128 v[182:185], v84 offset:4704
	v_mfma_f32_32x32x16_bf16 v[32:47], v[96:99], v[88:91], v[32:47]
	v_mfma_f32_32x32x16_bf16 v[16:31], v[128:131], v[88:91], v[16:31]
	v_mfma_f32_32x32x16_bf16 v[32:47], v[100:103], v[92:95], v[32:47]
	v_mfma_f32_32x32x16_bf16 v[16:31], v[132:135], v[92:95], v[16:31]
.Lv1p_body:
	s_cmp_gt_u32 s8, 61
	s_cselect_b64 s[78:79], -1, 0
	s_and_b64 vcc, exec, s[78:79]
	s_cbranch_vccnz .LBB0_625
	s_mul_i32 s16, s56, 0x9000
	s_add_i32 m0, s16, s35
	s_nop 0
	global_load_lds_dwordx4 v[240:241], off
	s_add_i32 m0, s16, s33
	v_lshl_add_u64 v[240:241], v[240:241], 0, v[200:201]
	global_load_lds_dwordx4 v[242:243], off
	s_add_i32 m0, s16, s93
	v_lshl_add_u64 v[242:243], v[242:243], 0, v[202:203]
	global_load_lds_dwordx4 v[244:245], off
	s_add_i32 m0, s16, s45
	v_lshl_add_u64 v[244:245], v[244:245], 0, v[204:205]
	global_load_lds_dwordx4 v[246:247], off
	s_mov_b32 m0, s27
	v_lshl_add_u64 v[246:247], v[246:247], 0, v[206:207]
	global_load_lds_dwordx4 v[248:249], off
	v_lshl_add_u64 v[248:249], v[248:249], 0, v[208:209]

.LBB0_639:
	s_add_i32 s50, s44, 0
	v_add3_u32 v84, s50, v162, v146
	ds_read_b128 v[80:83], v84
	ds_read_b128 v[128:131], v84 offset:32
	ds_read_b128 v[132:135], v84 offset:4608
	ds_read_b128 v[136:139], v84 offset:4640
	ds_read_b128 v[140:143], v84 offset:64
	ds_read_b128 v[220:223], v84 offset:96
	ds_read_b128 v[224:227], v84 offset:4672
	ds_read_b128 v[228:231], v84 offset:4704
	s_branch .Lv2p_body
.LBB0_638:
	s_cmpk_eq_i32 s20, 0xfc0
	s_cbranch_scc1 .Lv2p_flush
	s_add_i32 s50, s44, 0
	v_add3_u32 v84, s50, v162, v146
	ds_read_b128 v[80:83], v84
	ds_read_b128 v[128:131], v84 offset:32
	ds_read_b128 v[132:135], v84 offset:4608
	ds_read_b128 v[136:139], v84 offset:4640
	ds_read_b128 v[140:143], v84 offset:64
	ds_read_b128 v[220:223], v84 offset:96
	ds_read_b128 v[224:227], v84 offset:4672
	ds_read_b128 v[228:231], v84 offset:4704
	v_mfma_f32_32x32x16_bf16 v[32:47], v[182:185], v[170:173], v[32:47]
	v_add_f32_e32 v96, v97, v96
	v_add_f32_e32 v96, v98, v96
	v_add_f32_e32 v96, v99, v96
	v_add_f32_e32 v96, v100, v96
	v_mfma_f32_32x32x16_bf16 v[16:31], v[190:193], v[170:173], v[16:31]
	v_add_f32_e32 v96, v101, v96
	v_add_f32_e32 v96, v102, v96
	v_add_f32_e32 v96, v103, v96
	v_add_f32_e32 v96, v104, v96
	v_mfma_f32_32x32x16_bf16 v[32:47], v[186:189], v[178:181], v[32:47]
	v_add_f32_e32 v96, v105, v96
	v_add_f32_e32 v96, v106, v96
	v_add_f32_e32 v96, v107, v96
	v_add_f32_e32 v96, v108, v96
	v_mfma_f32_32x32x16_bf16 v[16:31], v[194:197], v[178:181], v[16:31]
	v_add_f32_e32 v96, v109, v96
	v_add_f32_e32 v96, v110, v96
	v_add_f32_e32 v96, v111, v96
	v_add_f32_e32 v96, v157, v96
	v_add_f32_e32 v157, v96, v251
.Lv2p_body:
	s_add_i32 s51, s27, s20
	s_add_i32 s4, s51, 64
	s_cmpk_lt_i32 s4, 0xff42
	s_cselect_b32 s5, 1, 0
	s_cmpk_gt_i32 s4, 0x9e
	s_cselect_b32 s4, 2, s5
	s_cmp_eq_u32 s4, s32
	s_cbranch_scc1 .Lattn_negm_keep_1
	s_mov_b32 s32, s4
	s_cmp_eq_u32 s4, 1
	s_cselect_b64 vcc, -1, 0
	s_cmp_eq_u32 s4, 2
	s_cselect_b64 s[4:5], -1, 0
	v_cndmask_b32_e64 v84, 0, v160, s[4:5]
	v_cndmask_b32_e32 v252, v84, v159, vcc
	v_sub_f32_e32 v84, v252, v156
	v_mov_b32_e32 v79, v84
	v_mov_b32_e32 v78, v84
	v_mov_b32_e32 v77, v84
	v_mov_b32_e32 v76, v84
	v_mov_b32_e32 v75, v84
	v_mov_b32_e32 v74, v84
	v_mov_b32_e32 v73, v84
	v_mov_b32_e32 v72, v84
	v_mov_b32_e32 v71, v84
	v_mov_b32_e32 v70, v84
	v_mov_b32_e32 v69, v84
	v_mov_b32_e32 v68, v84
	v_mov_b32_e32 v67, v84
	v_mov_b32_e32 v66, v84
	v_mov_b32_e32 v65, v84
	v_mov_b32_e32 v64, v84

.LBB0_683:
	v_add3_u32 v165, s57, v143, v163
	ds_read_b128 v[190:193], v165 offset:18432
	ds_read_b128 v[194:197], v165 offset:18448
	ds_read_b128 v[128:131], v165 offset:23040
	ds_read_b128 v[132:135], v165 offset:23056
	ds_read_b128 v[136:139], v165 offset:27648
	ds_read_b128 v[166:169], v165 offset:27664
	ds_read_b128 v[170:173], v165 offset:32256
	ds_read_b128 v[178:181], v165 offset:32272
	v_exp_f32_e32 v96, v96
	v_exp_f32_e32 v97, v97
	v_exp_f32_e32 v98, v98
	v_exp_f32_e32 v99, v99
	v_exp_f32_e32 v100, v100
	v_add_f32_e32 v198, v97, v96
	v_exp_f32_e32 v101, v101
	v_add_f32_e32 v198, v98, v198
	v_exp_f32_e32 v102, v102
	v_add_f32_e32 v198, v99, v198
	v_exp_f32_e32 v103, v103
	v_add_f32_e32 v198, v100, v198
	v_exp_f32_e32 v104, v104
	v_add_f32_e32 v198, v101, v198
	v_exp_f32_e32 v105, v105
	v_add_f32_e32 v198, v102, v198
	v_exp_f32_e32 v106, v106
	v_add_f32_e32 v198, v103, v198
	v_exp_f32_e32 v107, v107
	v_add_f32_e32 v198, v104, v198
	v_exp_f32_e32 v108, v108
	v_add_f32_e32 v198, v105, v198
	v_exp_f32_e32 v109, v109
	v_add_f32_e32 v198, v106, v198
	v_exp_f32_e32 v110, v110
	v_add_f32_e32 v198, v107, v198
	v_exp_f32_e32 v111, v111
	v_add_f32_e32 v198, v108, v198
	v_add_f32_e32 v198, v109, v198
	v_add_f32_e32 v198, v110, v198
	v_add_f32_e32 v198, v111, v198
	v_add_f32_e32 v157, v157, v198
	v_cvt_pk_bf16_f32 v96, v96, v97
	v_cvt_pk_bf16_f32 v97, v98, v99
	v_cvt_pk_bf16_f32 v98, v100, v101
	v_cvt_pk_bf16_f32 v99, v102, v103
	v_cvt_pk_bf16_f32 v100, v104, v105
	v_cvt_pk_bf16_f32 v101, v106, v107
	v_cvt_pk_bf16_f32 v102, v108, v109
	v_cvt_pk_bf16_f32 v103, v110, v111
	s_waitcnt lgkmcnt(7)
	v_mfma_f32_32x32x16_bf16 v[48:63], v[190:193], v[96:99], v[48:63]
	v_exp_f32_e32 v174, v80
	v_exp_f32_e32 v175, v81
	v_exp_f32_e32 v182, v82
	v_exp_f32_e32 v183, v83
	v_add_f32_e32 v80, v175, v174
	v_add_f32_e32 v80, v182, v80
	s_waitcnt lgkmcnt(5)
	v_mfma_f32_32x32x16_bf16 v[0:15], v[128:131], v[96:99], v[0:15]
	v_add_f32_e32 v80, v183, v80
	v_mfma_f32_32x32x16_bf16 v[48:63], v[194:197], v[100:103], v[48:63]
	v_exp_f32_e32 v128, v84
	v_exp_f32_e32 v129, v85
	v_exp_f32_e32 v130, v86
	v_exp_f32_e32 v131, v87
	v_add_f32_e32 v80, v128, v80
	v_add_f32_e32 v80, v129, v80
	v_add_f32_e32 v80, v130, v80
	s_waitcnt lgkmcnt(4)
	v_mfma_f32_32x32x16_bf16 v[0:15], v[132:135], v[100:103], v[0:15]
	v_add_f32_e32 v184, v131, v80
	ds_read_b128 v[80:83], v165 offset:18496
	ds_read_b128 v[84:87], v165 offset:18512
	ds_read_b128 v[104:107], v165 offset:23104
	ds_read_b128 v[108:111], v165 offset:23120
	s_waitcnt lgkmcnt(7)
	v_mfma_f32_32x32x16_bf16 v[32:47], v[136:139], v[96:99], v[32:47]
	v_exp_f32_e32 v132, v88
	v_exp_f32_e32 v133, v89
	v_exp_f32_e32 v134, v90
	v_exp_f32_e32 v135, v91
	v_add_f32_e32 v88, v132, v184
	v_add_f32_e32 v88, v133, v88
	v_add_f32_e32 v88, v134, v88
	s_waitcnt lgkmcnt(5)
	v_mfma_f32_32x32x16_bf16 v[16:31], v[170:173], v[96:99], v[16:31]
	v_add_f32_e32 v88, v135, v88
	v_exp_f32_e32 v96, v92
	v_mfma_f32_32x32x16_bf16 v[32:47], v[166:169], v[100:103], v[32:47]
	v_exp_f32_e32 v97, v93
	v_exp_f32_e32 v98, v94
	v_exp_f32_e32 v95, v95
	v_add_f32_e32 v88, v96, v88
	v_add_f32_e32 v88, v97, v88
	v_add_f32_e32 v88, v98, v88
	v_add_f32_e32 v88, v95, v88
	s_waitcnt lgkmcnt(4)
	v_mfma_f32_32x32x16_bf16 v[16:31], v[178:181], v[100:103], v[16:31]
	v_add_f32_e32 v157, v157, v88
	v_cvt_pk_bf16_f32 v88, v174, v175
	v_cvt_pk_bf16_f32 v89, v182, v183
	v_cvt_pk_bf16_f32 v90, v128, v129
	v_cvt_pk_bf16_f32 v91, v130, v131
	v_cvt_pk_bf16_f32 v92, v132, v133
	v_cvt_pk_bf16_f32 v93, v134, v135
	v_cvt_pk_bf16_f32 v94, v96, v97
	v_cvt_pk_bf16_f32 v95, v98, v95
	ds_read_b128 v[96:99], v165 offset:27712
	ds_read_b128 v[100:103], v165 offset:27728
	ds_read_b128 v[128:131], v165 offset:32320
	ds_read_b128 v[132:135], v165 offset:32336
	s_waitcnt lgkmcnt(7)
	v_mfma_f32_32x32x16_bf16 v[48:63], v[80:83], v[88:91], v[48:63]
	s_waitcnt lgkmcnt(5)
	v_mfma_f32_32x32x16_bf16 v[0:15], v[104:107], v[88:91], v[0:15]
	s_add_i32 s4, s9, 0x9000
	s_cmp_lg_u32 s9, 0x12000
	s_cselect_b32 s9, s4, 0
	s_add_i32 s4, s56, 1
	v_mfma_f32_32x32x16_bf16 v[48:63], v[84:87], v[92:95], v[48:63]
	s_waitcnt lgkmcnt(4)
	v_mfma_f32_32x32x16_bf16 v[0:15], v[108:111], v[92:95], v[0:15]
	s_cmp_lg_u32 s56, 2
	s_cselect_b32 s56, s4, 0
	s_add_i32 s8, s8, 1
	s_add_u32 s10, s10, 0x60000
	s_addc_u32 s11, s11, 0
	s_add_i32 s58, s58, 64
	s_cmpk_lg_i32 s58, 0x7c0
	s_waitcnt lgkmcnt(0)
	s_barrier
	s_cbranch_scc0 .Lv1s_flush
	s_add_i32 s57, s9, 0
	s_add_i32 s4, s57, s94
	v_add_u32_e32 v80, s4, v162
	v_add_u32_e32 v84, v80, v146
	ds_read_b128 v[80:83], v84
	ds_read_b128 v[220:223], v84 offset:32
	ds_read_b128 v[136:139], v84 offset:4608
	ds_read_b128 v[224:227], v84 offset:4640
	ds_read_b128 v[166:169], v84 offset:64
	ds_read_b128 v[170:173], v84 offset:96
	ds_read_b128 v[178:181], v84 offset:4672
	ds_read_b128 v[182:185], v84 offset:4704
	v_mfma_f32_32x32x16_bf16 v[32:47], v[96:99], v[88:91], v[32:47]
	v_mfma_f32_32x32x16_bf16 v[16:31], v[128:131], v[88:91], v[16:31]
	v_mfma_f32_32x32x16_bf16 v[32:47], v[100:103], v[92:95], v[32:47]
	v_mfma_f32_32x32x16_bf16 v[16:31], v[132:135], v[92:95], v[16:31]
.Lv1s_body:
	s_cmp_gt_u32 s8, 29
	s_cselect_b64 s[78:79], -1, 0
	s_and_b64 vcc, exec, s[78:79]
	s_cbranch_vccnz .LBB0_686
	s_mul_i32 vcc_lo, s56, 0x9000
	s_add_i32 m0, vcc_lo, s35
	s_nop 0
	global_load_lds_dwordx4 v[240:241], off
	s_add_i32 m0, vcc_lo, s33
	v_lshl_add_u64 v[240:241], v[240:241], 0, v[200:201]
	global_load_lds_dwordx4 v[242:243], off
	s_add_i32 m0, vcc_lo, s93
	v_lshl_add_u64 v[242:243], v[242:243], 0, v[202:203]
	global_load_lds_dwordx4 v[244:245], off
	s_add_i32 m0, vcc_lo, s45
	v_lshl_add_u64 v[244:245], v[244:245], 0, v[204:205]
	global_load_lds_dwordx4 v[246:247], off
	s_mov_b32 m0, s86
	v_lshl_add_u64 v[246:247], v[246:247], 0, v[206:207]
	global_load_lds_dwordx4 v[248:249], off
	v_lshl_add_u64 v[248:249], v[248:249], 0, v[208:209]

.LBB0_700:
	s_add_i32 s56, s44, 0
	v_add3_u32 v84, s56, v162, v146
	ds_read_b128 v[80:83], v84
	ds_read_b128 v[128:131], v84 offset:32
	ds_read_b128 v[132:135], v84 offset:4608
	ds_read_b128 v[136:139], v84 offset:4640
	ds_read_b128 v[140:143], v84 offset:64
	ds_read_b128 v[220:223], v84 offset:96
	ds_read_b128 v[224:227], v84 offset:4672
	ds_read_b128 v[228:231], v84 offset:4704
	s_branch .Lv2s_body
.LBB0_699:
	s_cmpk_eq_i32 s20, 0x7c0
	s_cbranch_scc1 .Lv2s_flush
	s_add_i32 s56, s44, 0
	v_add3_u32 v84, s56, v162, v146
	ds_read_b128 v[80:83], v84
	ds_read_b128 v[128:131], v84 offset:32
	ds_read_b128 v[132:135], v84 offset:4608
	ds_read_b128 v[136:139], v84 offset:4640
	ds_read_b128 v[140:143], v84 offset:64
	ds_read_b128 v[220:223], v84 offset:96
	ds_read_b128 v[224:227], v84 offset:4672
	ds_read_b128 v[228:231], v84 offset:4704
	v_mfma_f32_32x32x16_bf16 v[32:47], v[182:185], v[170:173], v[32:47]
	v_add_f32_e32 v96, v97, v96
	v_add_f32_e32 v96, v98, v96
	v_add_f32_e32 v96, v99, v96
	v_add_f32_e32 v96, v100, v96
	v_mfma_f32_32x32x16_bf16 v[16:31], v[190:193], v[170:173], v[16:31]
	v_add_f32_e32 v96, v101, v96
	v_add_f32_e32 v96, v102, v96
	v_add_f32_e32 v96, v103, v96
	v_add_f32_e32 v96, v104, v96
	v_mfma_f32_32x32x16_bf16 v[32:47], v[186:189], v[178:181], v[32:47]
	v_add_f32_e32 v96, v105, v96
	v_add_f32_e32 v96, v106, v96
	v_add_f32_e32 v96, v107, v96
	v_add_f32_e32 v96, v108, v96
	v_mfma_f32_32x32x16_bf16 v[16:31], v[194:197], v[178:181], v[16:31]
	v_add_f32_e32 v96, v109, v96
	v_add_f32_e32 v96, v110, v96
	v_add_f32_e32 v96, v111, v96
	v_add_f32_e32 v96, v157, v96
	v_add_f32_e32 v157, v96, v251
.Lv2s_body:
	s_add_i32 s16, s27, s20
	s_add_i32 s4, s16, 64
	s_cmpk_lt_i32 s4, 0xff42
	s_cselect_b32 s5, 1, 0
	s_cmpk_gt_i32 s4, 0x9e
	s_cselect_b32 s4, 2, s5
	s_cmp_eq_u32 s4, s32
	s_cbranch_scc1 .Lattn_negm_keep_3
	s_mov_b32 s32, s4
	s_cmp_eq_u32 s4, 1
	s_cselect_b64 vcc, -1, 0
	s_cmp_eq_u32 s4, 2
	s_cselect_b64 s[4:5], -1, 0
	v_cndmask_b32_e64 v84, 0, v160, s[4:5]
	v_cndmask_b32_e32 v252, v84, v159, vcc
	v_sub_f32_e32 v84, v252, v156
	v_mov_b32_e32 v79, v84
	v_mov_b32_e32 v78, v84
	v_mov_b32_e32 v77, v84
	v_mov_b32_e32 v76, v84
	v_mov_b32_e32 v75, v84
	v_mov_b32_e32 v74, v84
	v_mov_b32_e32 v73, v84
	v_mov_b32_e32 v72, v84
	v_mov_b32_e32 v71, v84
	v_mov_b32_e32 v70, v84
	v_mov_b32_e32 v69, v84
	v_mov_b32_e32 v68, v84
	v_mov_b32_e32 v67, v84
	v_mov_b32_e32 v66, v84
	v_mov_b32_e32 v65, v84
	v_mov_b32_e32 v64, v84
